# EpiUp: 8 of 12 conv-weight loads hoisted to the epilogue top in saddr form (latency covered by rstd scaling + halo exchange + barrier), dead ss-address code removed, vmcnt retargeted
# speedup vs baseline: 1.0093x; 1.0003x over previous
.LBB0_393:
	s_lshl_b32 s4, s27, 8
	v_mov_b32_e32 v167, v250
	v_mov_b32_e32 v166, v249
	s_add_i32 s4, s4, s96
	s_nop 0
	v_lshl_add_u32 v232, v166, 3, s4
	v_lshl_add_u32 v202, v250, 3, s89
	v_lshlrev_b32_e32 v202, 2, v202
	s_lshl_b32 s100, s26, 9
	s_add_u32 s100, s48, s100
	s_addc_u32 s101, s49, 0
	global_load_dwordx4 v[158:161], v202, s[100:101]
	global_load_dwordx4 v[190:193], v202, s[100:101] offset:16
	s_add_u32 s100, s100, 0x5000
	s_addc_u32 s101, s101, 0
	global_load_dwordx4 v[162:165], v202, s[100:101] offset:2048
	global_load_dwordx4 v[194:197], v202, s[100:101] offset:2064
	s_add_u32 s100, s100, 0x3000
	s_addc_u32 s101, s101, 0
	global_load_dwordx4 v[146:149], v202, s[100:101] offset:1024
	s_add_u32 s100, s100, 0x3000
	s_addc_u32 s101, s101, 0
	global_load_dwordx4 v[174:177], v202, s[100:101]
	global_load_dwordx4 v[198:201], v202, s[100:101] offset:16
	s_add_u32 s100, s100, 0x2000
	s_addc_u32 s101, s101, 0
	global_load_dwordx4 v[150:153], v202, s[100:101] offset:3072
	s_add_i32 s4, s58, -1
	s_lshl_b32 s4, s4, 10
	s_add_i32 s4, s4, 0x21000
	v_lshrrev_b32_e32 v136, 8, v248
	v_lshlrev_b32_e32 v136, 9, v136
	v_lshl_add_u32 v136, v249, 5, v136
	v_add_u32_e32 v136, s4, v136
	ds_read_b32 v134, v136
	ds_read_b32 v135, v136 offset:4
	ds_read_b32 v240, v136 offset:8
	ds_read_b32 v242, v136 offset:12
	ds_read_b32 v236, v136 offset:16
	ds_read_b32 v238, v136 offset:20
	ds_read_b32 v130, v136 offset:24
	ds_read_b32 v131, v136 offset:28
	s_waitcnt lgkmcnt(0)
	v_lshl_add_u32 v138, v167, 3, s89
	v_ashrrev_i32_e32 v139, 31, v138
	s_waitcnt lgkmcnt(0)
	s_waitcnt lgkmcnt(0)
	s_nop 0
	s_nop 0
	s_nop 0
	s_nop 0
	v_pk_mul_f32 v[116:117], v[116:117], v[134:135] op_sel_hi:[1,0]
	v_pk_mul_f32 v[114:115], v[114:115], v[134:135] op_sel_hi:[1,0]
	v_pk_mul_f32 v[124:125], v[124:125], v[134:135] op_sel_hi:[1,0]
	v_pk_mul_f32 v[122:123], v[122:123], v[134:135] op_sel_hi:[1,0]
	v_pk_mul_f32 v[108:109], v[108:109], v[134:135] op_sel_hi:[1,0]
	v_pk_mul_f32 v[106:107], v[106:107], v[134:135] op_sel_hi:[1,0]
	v_pk_mul_f32 v[44:45], v[44:45], v[134:135] op_sel_hi:[1,0]
	v_pk_mul_f32 v[42:43], v[42:43], v[134:135] op_sel_hi:[1,0]
	s_nop 0
	v_mov_b32_e32 v134, v135
	v_pk_mul_f32 v[120:121], v[120:121], v[134:135] op_sel_hi:[1,0]
	v_pk_mul_f32 v[118:119], v[118:119], v[134:135] op_sel_hi:[1,0]
	v_pk_mul_f32 v[128:129], v[128:129], v[134:135] op_sel_hi:[1,0]
	v_pk_mul_f32 v[126:127], v[126:127], v[134:135] op_sel_hi:[1,0]
	v_pk_mul_f32 v[112:113], v[112:113], v[134:135] op_sel_hi:[1,0]
	v_pk_mul_f32 v[110:111], v[110:111], v[134:135] op_sel_hi:[1,0]
	v_pk_mul_f32 v[48:49], v[48:49], v[134:135] op_sel_hi:[1,0]
	v_pk_mul_f32 v[46:47], v[46:47], v[134:135] op_sel_hi:[1,0]
	s_nop 0
	s_nop 0
	s_nop 0
	s_waitcnt lgkmcnt(0)
	s_waitcnt lgkmcnt(2)
	v_or_b32_e32 v134, s71, v166
	v_cmp_eq_u32_e32 vcc, 0, v134
	s_waitcnt lgkmcnt(0)
	s_and_saveexec_b64 s[38:39], vcc
	s_cbranch_execz .LBB0_395
	s_lshl_b32 s4, s26, 8
	s_ashr_i32 s5, s4, 31
	s_mul_i32 s7, s27, 0x16000
	s_mul_hi_i32 s6, s27, 0x16000
	s_add_u32 s7, s84, s7
	s_addc_u32 s6, s88, s6
	s_lshl_b64 s[4:5], s[4:5], 2
	s_add_u32 s4, s7, s4
	s_addc_u32 s5, s6, s5
	v_lshl_add_u64 v[134:135], v[138:139], 2, s[4:5]
	s_mov_b64 s[4:5], 0x5800
	global_store_dwordx4 v[134:135], v[114:117], off
	global_store_dwordx4 v[134:135], v[122:125], off offset:16
	global_store_dwordx4 v[134:135], v[106:109], off offset:512
	global_store_dwordx4 v[134:135], v[42:45], off offset:528
	v_lshl_add_u64 v[136:137], v[134:135], 0, s[4:5]
	v_add_co_u32_e32 v134, vcc, 0x5000, v134
	s_nop 1
	v_addc_co_u32_e32 v135, vcc, 0, v135, vcc
	global_store_dwordx4 v[134:135], v[118:121], off offset:2048
	global_store_dwordx4 v[136:137], v[126:129], off offset:16
	global_store_dwordx4 v[136:137], v[110:113], off offset:512
	global_store_dwordx4 v[136:137], v[46:49], off offset:528

.LBB0_400:
	s_mov_b32 s100, 0xbfb8aa3b
	s_or_b64 exec, exec, s[38:39]
	s_ashr_i32 s27, s26, 31
	s_lshl_b64 s[4:5], s[26:27], 7
	v_lshl_add_u64 v[234:235], s[4:5], 0, v[138:139]
	v_lshl_add_u64 v[86:87], v[234:235], 2, s[48:49]
	s_waitcnt lgkmcnt(0)
	s_barrier
	v_mov_b32_dpp v90, v135 row_shr:1 row_mask:0xf bank_mask:0xf bound_ctrl:1
	v_add_co_u32_e32 v80, vcc, s80, v86
	v_mov_b32_dpp v91, v144 row_shr:1 row_mask:0xf bank_mask:0xf bound_ctrl:1
	s_nop 0
	v_addc_co_u32_e32 v81, vcc, 0, v87, vcc
	v_add_co_u32_e32 v88, vcc, s64, v86
	global_load_dwordx4 v[138:141], v[80:81], off offset:3072
	v_addc_co_u32_e32 v89, vcc, 0, v87, vcc
	v_mov_b32_dpp v80, v134 row_shr:1 row_mask:0xf bank_mask:0xf bound_ctrl:1
	v_lshlrev_b32_e32 v78, 7, v167
	v_mov_b32_dpp v79, v142 row_shr:1 row_mask:0xf bank_mask:0xf bound_ctrl:1
	v_mov_b32_dpp v81, v143 row_shr:1 row_mask:0xf bank_mask:0xf bound_ctrl:1
	v_mov_b32_dpp v92, v136 row_shr:1 row_mask:0xf bank_mask:0xf bound_ctrl:1
	v_mov_b32_dpp v93, v145 row_shr:1 row_mask:0xf bank_mask:0xf bound_ctrl:1
	v_mov_b32_dpp v94, v137 row_shr:1 row_mask:0xf bank_mask:0xf bound_ctrl:1
	v_cmp_ne_u32_e64 s[42:43], 0, v166
	s_nor_b64 s[26:27], s[52:53], s[42:43]
	v_add_u32_e32 v233, s97, v78
	v_cndmask_b32_e64 v185, 0, v93, s[42:43]
	v_cndmask_b32_e64 v184, 0, v91, s[42:43]
	v_cndmask_b32_e64 v183, 0, v81, s[42:43]
	v_cndmask_b32_e64 v182, 0, v79, s[42:43]
	v_cndmask_b32_e64 v189, 0, v94, s[42:43]
	v_cndmask_b32_e64 v188, 0, v92, s[42:43]
	v_cndmask_b32_e64 v187, 0, v90, s[42:43]
	v_cndmask_b32_e64 v186, 0, v80, s[42:43]
	s_and_saveexec_b64 s[38:39], s[26:27]
	s_cbranch_execz .LBB0_402
	ds_read_b128 v[186:189], v233
	ds_read_b128 v[182:185], v233 offset:64

.LBB0_404:
	s_or_b64 exec, exec, s[38:39]
	v_add_co_u32_e32 v80, vcc, 0x2000, v86
	s_nop 0
	v_addc_co_u32_e32 v81, vcc, 0, v87, vcc
	v_add_co_u32_e32 v90, vcc, 0xd000, v86
	s_nop 0
	global_load_dwordx4 v[78:81], v[80:81], off offset:3088
	v_addc_co_u32_e32 v91, vcc, 0, v87, vcc
	global_load_dwordx4 v[86:89], v[88:89], off offset:1040
	s_nop 0
	global_load_dwordx4 v[90:93], v[90:91], off offset:3088
	v_mov_b32_dpp v205, v181 row_shr:1 row_mask:0xf bank_mask:0xf bound_ctrl:1
	v_mov_b32_dpp v204, v180 row_shr:1 row_mask:0xf bank_mask:0xf bound_ctrl:1
	v_mov_b32_dpp v203, v179 row_shr:1 row_mask:0xf bank_mask:0xf bound_ctrl:1
	v_mov_b32_dpp v202, v178 row_shr:1 row_mask:0xf bank_mask:0xf bound_ctrl:1
	v_mov_b32_dpp v209, v157 row_shr:1 row_mask:0xf bank_mask:0xf bound_ctrl:1
	v_mov_b32_dpp v208, v156 row_shr:1 row_mask:0xf bank_mask:0xf bound_ctrl:1
	v_mov_b32_dpp v207, v155 row_shr:1 row_mask:0xf bank_mask:0xf bound_ctrl:1
	v_mov_b32_dpp v206, v154 row_shr:1 row_mask:0xf bank_mask:0xf bound_ctrl:1
	s_and_saveexec_b64 s[38:39], s[26:27]
	s_cbranch_execz .LBB0_406
	ds_read_b128 v[206:209], v233 offset:16
	ds_read_b128 v[202:205], v233 offset:80

.LBB0_408:
	s_or_b64 exec, exec, s[38:39]
	s_mov_b32 s4, 0x358637bd
	v_mov_b64_e32 v[214:215], s[4:5]
	s_mov_b64 s[26:27], -1
	v_pk_mul_f32 v[16:17], v[16:17], v[240:241] op_sel_hi:[1,0]
	v_pk_mul_f32 v[220:221], v[68:69], v[242:243] op_sel_hi:[1,0]
	v_pk_mul_f32 v[218:219], v[66:67], v[242:243] op_sel_hi:[1,0]
	v_pk_mul_f32 v[216:217], v[72:73], v[240:241] op_sel_hi:[1,0]
	v_pk_mul_f32 v[72:73], v[64:65], v[236:237] op_sel_hi:[1,0]
	s_waitcnt vmcnt(4)
	v_pk_mul_f32 v[64:65], v[154:155], v[198:199]
	v_pk_mul_f32 v[68:69], v[60:61], v[238:239] op_sel_hi:[1,0]
	v_pk_mul_f32 v[60:61], v[178:179], v[198:199]
	v_pk_mul_f32 v[66:67], v[58:59], v[238:239] op_sel_hi:[1,0]
	v_pk_mul_f32 v[58:59], v[180:181], v[200:201]
	v_pk_fma_f32 v[60:61], v[154:155], v[194:195], v[60:61]
	v_pk_mul_f32 v[214:215], v[70:71], v[240:241] op_sel_hi:[1,0]
	v_pk_mul_f32 v[70:71], v[62:63], v[236:237] op_sel_hi:[1,0]
	v_pk_fma_f32 v[58:59], v[156:157], v[196:197], v[58:59]
	v_pk_fma_f32 v[60:61], v[66:67], v[190:191], v[60:61]
	v_pk_mul_f32 v[62:63], v[156:157], v[200:201]
	v_pk_fma_f32 v[64:65], v[66:67], v[194:195], v[64:65]
	v_pk_mul_f32 v[66:67], v[66:67], v[198:199]
	v_pk_fma_f32 v[58:59], v[68:69], v[192:193], v[58:59]
	v_pk_fma_f32 v[62:63], v[68:69], v[196:197], v[62:63]
	v_pk_fma_f32 v[64:65], v[70:71], v[190:191], v[64:65]
	v_pk_mul_f32 v[68:69], v[68:69], v[200:201]
	v_pk_fma_f32 v[154:155], v[70:71], v[194:195], v[66:67]
	v_pk_mul_f32 v[70:71], v[70:71], v[198:199]
	v_pk_fma_f32 v[62:63], v[72:73], v[192:193], v[62:63]
	v_pk_fma_f32 v[66:67], v[72:73], v[196:197], v[68:69]
	v_pk_fma_f32 v[68:69], v[218:219], v[190:191], v[154:155]
	v_pk_mul_f32 v[72:73], v[72:73], v[200:201]
	v_pk_fma_f32 v[154:155], v[218:219], v[194:195], v[70:71]
	v_pk_fma_f32 v[70:71], v[220:221], v[196:197], v[72:73]
	v_pk_fma_f32 v[72:73], v[214:215], v[190:191], v[154:155]
	v_pk_mul_f32 v[154:155], v[220:221], v[200:201]
	v_pk_mul_f32 v[156:157], v[218:219], v[198:199]
	v_pk_fma_f32 v[154:155], v[216:217], v[196:197], v[154:155]
	v_pk_fma_f32 v[156:157], v[214:215], v[194:195], v[156:157]
	v_pk_mul_f32 v[178:179], v[216:217], v[200:201]
	v_pk_mul_f32 v[180:181], v[214:215], v[198:199]
	v_pk_fma_f32 v[154:155], v[128:129], v[192:193], v[154:155]
	v_pk_fma_f32 v[156:157], v[126:127], v[190:191], v[156:157]
	v_pk_fma_f32 v[180:181], v[126:127], v[194:195], v[180:181]
	v_pk_fma_f32 v[178:179], v[128:129], v[196:197], v[178:179]
	v_pk_mul_f32 v[128:129], v[128:129], v[200:201]
	v_pk_mul_f32 v[126:127], v[126:127], v[198:199]
	v_pk_fma_f32 v[128:129], v[124:125], v[196:197], v[128:129]
	v_pk_fma_f32 v[214:215], v[122:123], v[194:195], v[126:127]
	s_waitcnt lgkmcnt(0)
	v_pk_mul_f32 v[196:197], v[196:197], v[204:205]
	v_pk_mul_f32 v[194:195], v[194:195], v[202:203]
	v_pk_fma_f32 v[178:179], v[124:125], v[192:193], v[178:179]
	v_pk_fma_f32 v[124:125], v[124:125], v[200:201], v[196:197]
	v_pk_fma_f32 v[194:195], v[122:123], v[198:199], v[194:195]
	v_pk_mul_f32 v[198:199], v[38:39], v[236:237] op_sel_hi:[1,0]
	v_pk_mul_f32 v[200:201], v[40:41], v[236:237] op_sel_hi:[1,0]
	v_pk_mul_f32 v[38:39], v[144:145], v[176:177]
	v_pk_mul_f32 v[40:41], v[142:143], v[174:175]
	v_pk_mul_f32 v[34:35], v[34:35], v[238:239] op_sel_hi:[1,0]
	v_pk_mul_f32 v[36:37], v[36:37], v[238:239] op_sel_hi:[1,0]
	v_pk_fma_f32 v[38:39], v[136:137], v[164:165], v[38:39]
	v_pk_fma_f32 v[40:41], v[134:135], v[162:163], v[40:41]
	v_pk_fma_f32 v[66:67], v[220:221], v[192:193], v[66:67]
	v_pk_fma_f32 v[70:71], v[216:217], v[192:193], v[70:71]
	v_pk_fma_f32 v[180:181], v[122:123], v[190:191], v[180:181]
	v_pk_fma_f32 v[126:127], v[192:193], v[204:205], v[128:129]
	v_pk_fma_f32 v[128:129], v[190:191], v[202:203], v[214:215]
	v_pk_fma_f32 v[122:123], v[192:193], v[208:209], v[124:125]
	v_pk_fma_f32 v[124:125], v[190:191], v[206:207], v[194:195]
	v_pk_mul_f32 v[190:191], v[54:55], v[240:241] op_sel_hi:[1,0]
	v_pk_mul_f32 v[192:193], v[56:57], v[240:241] op_sel_hi:[1,0]
	v_pk_fma_f32 v[56:57], v[36:37], v[160:161], v[38:39]
	v_pk_fma_f32 v[54:55], v[34:35], v[158:159], v[40:41]
	v_pk_mul_f32 v[38:39], v[136:137], v[176:177]
	v_pk_mul_f32 v[40:41], v[134:135], v[174:175]
	v_pk_fma_f32 v[38:39], v[36:37], v[164:165], v[38:39]
	v_pk_fma_f32 v[40:41], v[34:35], v[162:163], v[40:41]
	v_pk_mul_f32 v[36:37], v[36:37], v[176:177]
	v_pk_mul_f32 v[34:35], v[34:35], v[174:175]
	v_pk_mul_f32 v[194:195], v[50:51], v[242:243] op_sel_hi:[1,0]
	v_pk_mul_f32 v[196:197], v[52:53], v[242:243] op_sel_hi:[1,0]
	v_pk_fma_f32 v[34:35], v[198:199], v[162:163], v[34:35]
	v_pk_fma_f32 v[36:37], v[200:201], v[164:165], v[36:37]
	v_pk_fma_f32 v[52:53], v[200:201], v[160:161], v[38:39]
	v_pk_fma_f32 v[50:51], v[198:199], v[158:159], v[40:41]
	v_pk_fma_f32 v[40:41], v[196:197], v[160:161], v[36:37]
	v_pk_fma_f32 v[38:39], v[194:195], v[158:159], v[34:35]
	v_pk_mul_f32 v[34:35], v[200:201], v[176:177]
	v_pk_mul_f32 v[36:37], v[198:199], v[174:175]
	v_pk_fma_f32 v[34:35], v[196:197], v[164:165], v[34:35]
	v_pk_fma_f32 v[134:135], v[194:195], v[162:163], v[36:37]
	v_pk_mul_f32 v[136:137], v[194:195], v[174:175]
	v_pk_fma_f32 v[36:37], v[192:193], v[160:161], v[34:35]
	v_pk_fma_f32 v[34:35], v[190:191], v[158:159], v[134:135]
	v_pk_mul_f32 v[134:135], v[196:197], v[176:177]
	v_pk_fma_f32 v[136:137], v[190:191], v[162:163], v[136:137]
	v_pk_mul_f32 v[144:145], v[190:191], v[174:175]
	v_pk_fma_f32 v[134:135], v[192:193], v[164:165], v[134:135]
	v_pk_fma_f32 v[136:137], v[118:119], v[158:159], v[136:137]
	v_pk_mul_f32 v[142:143], v[192:193], v[176:177]
	v_pk_fma_f32 v[144:145], v[118:119], v[162:163], v[144:145]
	v_pk_mul_f32 v[118:119], v[118:119], v[174:175]
	v_pk_fma_f32 v[134:135], v[120:121], v[160:161], v[134:135]
	v_pk_fma_f32 v[142:143], v[120:121], v[164:165], v[142:143]
	v_pk_mul_f32 v[120:121], v[120:121], v[176:177]
	v_pk_fma_f32 v[118:119], v[114:115], v[162:163], v[118:119]
	v_pk_fma_f32 v[120:121], v[116:117], v[164:165], v[120:121]
	v_pk_fma_f32 v[192:193], v[158:159], v[182:183], v[118:119]
	v_pk_mul_f32 v[118:119], v[164:165], v[184:185]
	v_pk_mul_f32 v[164:165], v[30:31], v[240:241] op_sel_hi:[1,0]
	v_pk_mul_f32 v[30:31], v[132:133], v[152:153]
	v_pk_fma_f32 v[142:143], v[116:117], v[160:161], v[142:143]
	v_pk_fma_f32 v[116:117], v[116:117], v[176:177], v[118:119]
	v_pk_mul_f32 v[20:21], v[20:21], v[238:239] op_sel_hi:[1,0]
	v_pk_fma_f32 v[30:31], v[104:105], v[148:149], v[30:31]
	v_pk_fma_f32 v[190:191], v[160:161], v[184:185], v[120:121]
	v_pk_fma_f32 v[160:161], v[160:161], v[188:189], v[116:117]
	s_waitcnt vmcnt(3)
	v_pk_fma_f32 v[116:117], v[20:21], v[140:141], v[30:31]
	v_pk_mul_f32 v[30:31], v[104:105], v[152:153]
	v_pk_mul_f32 v[120:121], v[162:163], v[182:183]
	v_pk_mul_f32 v[162:163], v[32:33], v[240:241] op_sel_hi:[1,0]
	v_pk_mul_f32 v[24:25], v[24:25], v[236:237] op_sel_hi:[1,0]
	v_pk_mul_f32 v[32:33], v[130:131], v[150:151]
	v_pk_fma_f32 v[30:31], v[20:21], v[148:149], v[30:31]
	v_pk_mul_f32 v[20:21], v[20:21], v[152:153]
	v_pk_fma_f32 v[144:145], v[114:115], v[158:159], v[144:145]
	v_pk_fma_f32 v[114:115], v[114:115], v[174:175], v[120:121]
	v_pk_mul_f32 v[28:29], v[28:29], v[242:243] op_sel_hi:[1,0]
	v_pk_mul_f32 v[18:19], v[18:19], v[238:239] op_sel_hi:[1,0]
	v_pk_fma_f32 v[32:33], v[102:103], v[146:147], v[32:33]
	v_pk_fma_f32 v[20:21], v[24:25], v[148:149], v[20:21]
	v_pk_fma_f32 v[158:159], v[158:159], v[186:187], v[114:115]
	v_pk_fma_f32 v[114:115], v[18:19], v[138:139], v[32:33]
	v_pk_mul_f32 v[32:33], v[102:103], v[150:151]
	v_pk_fma_f32 v[120:121], v[28:29], v[140:141], v[20:21]
	v_pk_mul_f32 v[20:21], v[24:25], v[152:153]
	v_pk_mul_f32 v[22:23], v[22:23], v[236:237] op_sel_hi:[1,0]
	v_pk_fma_f32 v[32:33], v[18:19], v[146:147], v[32:33]
	v_pk_mul_f32 v[18:19], v[18:19], v[150:151]
	v_pk_fma_f32 v[20:21], v[28:29], v[148:149], v[20:21]
	v_pk_mul_f32 v[26:27], v[26:27], v[242:243] op_sel_hi:[1,0]
	v_pk_fma_f32 v[18:19], v[22:23], v[146:147], v[18:19]
	v_pk_fma_f32 v[132:133], v[162:163], v[140:141], v[20:21]
	v_pk_mul_f32 v[20:21], v[28:29], v[152:153]
	v_pk_fma_f32 v[118:119], v[26:27], v[138:139], v[18:19]
	v_pk_mul_f32 v[18:19], v[22:23], v[150:151]
	v_pk_fma_f32 v[20:21], v[162:163], v[148:149], v[20:21]
	v_pk_fma_f32 v[102:103], v[22:23], v[138:139], v[32:33]
	v_pk_fma_f32 v[18:19], v[26:27], v[146:147], v[18:19]
	v_pk_fma_f32 v[32:33], v[112:113], v[140:141], v[20:21]
	v_pk_mul_f32 v[20:21], v[162:163], v[152:153]
	v_pk_fma_f32 v[130:131], v[164:165], v[138:139], v[18:19]
	v_pk_mul_f32 v[18:19], v[26:27], v[150:151]
	v_pk_fma_f32 v[20:21], v[112:113], v[148:149], v[20:21]
	v_pk_fma_f32 v[18:19], v[164:165], v[146:147], v[18:19]
	v_pk_fma_f32 v[28:29], v[108:109], v[140:141], v[20:21]
	v_pk_mul_f32 v[20:21], v[110:111], v[150:151]
	v_pk_fma_f32 v[104:105], v[24:25], v[140:141], v[30:31]
	v_pk_fma_f32 v[30:31], v[110:111], v[138:139], v[18:19]
	v_pk_mul_f32 v[18:19], v[164:165], v[150:151]
	v_pk_fma_f32 v[20:21], v[106:107], v[146:147], v[20:21]
	v_pk_fma_f32 v[18:19], v[110:111], v[146:147], v[18:19]
	v_pk_fma_f32 v[24:25], v[138:139], v[166:167], v[20:21]
	v_pk_mul_f32 v[20:21], v[146:147], v[166:167]
	v_pk_fma_f32 v[26:27], v[106:107], v[138:139], v[18:19]
	v_pk_fma_f32 v[20:21], v[106:107], v[150:151], v[20:21]
	v_pk_mul_f32 v[106:107], v[158:159], s[100:101] op_sel_hi:[1,0]
	v_exp_f32_e32 v106, v106
	v_exp_f32_e32 v107, v107
	v_pk_mul_f32 v[18:19], v[112:113], v[152:153]
	v_pk_fma_f32 v[20:21], v[138:139], v[170:171], v[20:21]
	v_pk_fma_f32 v[18:19], v[108:109], v[148:149], v[18:19]
	v_pk_add_f32 v[106:107], v[106:107], 1.0 op_sel_hi:[1,0]
	v_pk_fma_f32 v[22:23], v[140:141], v[168:169], v[18:19]
	v_pk_mul_f32 v[18:19], v[148:149], v[168:169]
	v_rcp_f32_e32 v106, v106
	v_rcp_f32_e32 v107, v107
	v_pk_fma_f32 v[18:19], v[108:109], v[152:153], v[18:19]
	v_pk_mul_f32 v[26:27], v[144:145], v[26:27]
	v_pk_fma_f32 v[18:19], v[140:141], v[172:173], v[18:19]
	v_pk_mul_f32 v[28:29], v[142:143], v[28:29]
	v_pk_mul_f32 v[108:109], v[160:161], v[18:19]
	v_pk_mul_f32 v[18:19], v[158:159], v[20:21]
	v_pk_mul_f32 v[20:21], v[160:161], s[100:101] op_sel_hi:[1,0]
	v_pk_mul_f32 v[18:19], v[106:107], v[18:19]
	v_exp_f32_e32 v20, v20
	v_exp_f32_e32 v21, v21
	v_pk_mul_f32 v[106:107], v[192:193], s[100:101] op_sel_hi:[1,0]
	v_exp_f32_e32 v106, v106
	v_exp_f32_e32 v107, v107
	v_pk_add_f32 v[20:21], v[20:21], 1.0 op_sel_hi:[1,0]
	v_rcp_f32_e32 v20, v20
	v_rcp_f32_e32 v21, v21
	v_pk_add_f32 v[106:107], v[106:107], 1.0 op_sel_hi:[1,0]
	v_rcp_f32_e32 v106, v106
	v_rcp_f32_e32 v107, v107
	v_pk_mul_f32 v[20:21], v[20:21], v[108:109]
	v_pk_mul_f32 v[108:109], v[190:191], v[22:23]
	v_pk_mul_f32 v[22:23], v[192:193], v[24:25]
	v_pk_mul_f32 v[30:31], v[136:137], v[30:31]
	v_pk_mul_f32 v[22:23], v[106:107], v[22:23]
	v_pk_mul_f32 v[106:107], v[144:145], s[100:101] op_sel_hi:[1,0]
	v_exp_f32_e32 v106, v106
	v_exp_f32_e32 v107, v107
	v_pk_mul_f32 v[24:25], v[190:191], s[100:101] op_sel_hi:[1,0]
	v_pk_add_f32 v[106:107], v[106:107], 1.0 op_sel_hi:[1,0]
	v_rcp_f32_e32 v106, v106
	v_rcp_f32_e32 v107, v107
	v_pk_mul_f32 v[32:33], v[134:135], v[32:33]
	v_exp_f32_e32 v24, v24
	v_exp_f32_e32 v25, v25
	v_pk_mul_f32 v[26:27], v[106:107], v[26:27]
	v_pk_mul_f32 v[106:107], v[142:143], s[100:101] op_sel_hi:[1,0]
	v_exp_f32_e32 v106, v106
	v_exp_f32_e32 v107, v107
	v_pk_add_f32 v[24:25], v[24:25], 1.0 op_sel_hi:[1,0]
	v_pk_add_f32 v[106:107], v[106:107], 1.0 op_sel_hi:[1,0]
	v_rcp_f32_e32 v106, v106
	v_rcp_f32_e32 v107, v107
	v_rcp_f32_e32 v24, v24
	v_rcp_f32_e32 v25, v25
	v_pk_mul_f32 v[104:105], v[52:53], v[104:105]
	v_pk_mul_f32 v[28:29], v[106:107], v[28:29]
	v_pk_mul_f32 v[106:107], v[136:137], s[100:101] op_sel_hi:[1,0]
	v_exp_f32_e32 v106, v106
	v_exp_f32_e32 v107, v107
	v_pk_mul_f32 v[24:25], v[24:25], v[108:109]
	v_pk_mul_f32 v[108:109], v[36:37], v[132:133]
	v_pk_add_f32 v[106:107], v[106:107], 1.0 op_sel_hi:[1,0]
	v_rcp_f32_e32 v106, v106
	v_rcp_f32_e32 v107, v107
	v_pk_mul_f32 v[36:37], v[36:37], s[100:101] op_sel_hi:[1,0]
	v_exp_f32_e32 v36, v36
	v_pk_mul_f32 v[30:31], v[106:107], v[30:31]
	v_pk_mul_f32 v[106:107], v[134:135], s[100:101] op_sel_hi:[1,0]
	v_exp_f32_e32 v106, v106
	v_exp_f32_e32 v107, v107
	v_exp_f32_e32 v37, v37
	v_mul_f32_e32 v52, 0xbfb8aa3b, v52
	v_pk_add_f32 v[106:107], v[106:107], 1.0 op_sel_hi:[1,0]
	v_rcp_f32_e32 v106, v106
	v_rcp_f32_e32 v107, v107
	v_mul_f32_e32 v53, 0xbfb8aa3b, v53
	v_exp_f32_e32 v52, v52
	v_exp_f32_e32 v53, v53
	v_pk_mul_f32 v[32:33], v[106:107], v[32:33]
	v_pk_mul_f32 v[106:107], v[34:35], s[100:101] op_sel_hi:[1,0]
	v_exp_f32_e32 v106, v106
	v_exp_f32_e32 v107, v107
	v_pk_mul_f32 v[34:35], v[34:35], v[130:131]
	v_add_f32_e32 v36, 1.0, v36
	v_pk_add_f32 v[106:107], v[106:107], 1.0 op_sel_hi:[1,0]
	v_rcp_f32_e32 v106, v106
	v_rcp_f32_e32 v107, v107
	v_add_f32_e32 v37, 1.0, v37
	v_rcp_f32_e32 v36, v36
	v_rcp_f32_e32 v37, v37
	v_pk_mul_f32 v[34:35], v[106:107], v[34:35]
	v_pk_mul_f32 v[106:107], v[38:39], s[100:101] op_sel_hi:[1,0]
	v_exp_f32_e32 v106, v106
	v_exp_f32_e32 v107, v107
	v_pk_add_f32 v[52:53], v[52:53], 1.0 op_sel_hi:[1,0]
	v_pk_add_f32 v[106:107], v[106:107], 1.0 op_sel_hi:[1,0]
	v_rcp_f32_e32 v106, v106
	v_rcp_f32_e32 v107, v107
	v_rcp_f32_e32 v52, v52
	v_rcp_f32_e32 v53, v53
	v_pk_mul_f32 v[36:37], v[36:37], v[108:109]
	v_pk_mul_f32 v[108:109], v[40:41], v[120:121]
	v_pk_mul_f32 v[38:39], v[38:39], v[118:119]
	v_pk_mul_f32 v[40:41], v[40:41], s[100:101] op_sel_hi:[1,0]
	v_pk_mul_f32 v[38:39], v[106:107], v[38:39]
	v_exp_f32_e32 v40, v40
	v_exp_f32_e32 v41, v41
	v_pk_mul_f32 v[106:107], v[50:51], s[100:101] op_sel_hi:[1,0]
	v_pk_mul_f32 v[50:51], v[50:51], v[102:103]
	v_pk_mul_f32 v[52:53], v[52:53], v[104:105]
	v_pk_mul_f32 v[102:103], v[54:55], s[100:101] op_sel_hi:[1,0]
	v_pk_mul_f32 v[104:105], v[56:57], v[116:117]
	v_pk_mul_f32 v[56:57], v[56:57], s[100:101] op_sel_hi:[1,0]
	v_exp_f32_e32 v102, v102
	v_exp_f32_e32 v103, v103
	v_exp_f32_e32 v56, v56
	v_exp_f32_e32 v57, v57
	v_exp_f32_e32 v106, v106
	v_exp_f32_e32 v107, v107
	v_pk_add_f32 v[40:41], v[40:41], 1.0 op_sel_hi:[1,0]
	v_rcp_f32_e32 v40, v40
	v_rcp_f32_e32 v41, v41
	v_pk_add_f32 v[102:103], v[102:103], 1.0 op_sel_hi:[1,0]
	v_pk_add_f32 v[56:57], v[56:57], 1.0 op_sel_hi:[1,0]
	v_rcp_f32_e32 v102, v102
	v_rcp_f32_e32 v103, v103
	v_rcp_f32_e32 v56, v56
	v_rcp_f32_e32 v57, v57
	v_pk_add_f32 v[106:107], v[106:107], 1.0 op_sel_hi:[1,0]
	v_rcp_f32_e32 v106, v106
	v_rcp_f32_e32 v107, v107
	v_pk_mul_f32 v[40:41], v[40:41], v[108:109]
	v_pk_mul_f32 v[54:55], v[54:55], v[114:115]
	v_pk_mul_f32 v[108:109], v[2:3], v[238:239] op_sel_hi:[1,0]
	s_waitcnt vmcnt(0)
	v_pk_mul_f32 v[2:3], v[76:77], v[92:93]
	v_pk_mul_f32 v[54:55], v[102:103], v[54:55]
	v_pk_mul_f32 v[56:57], v[56:57], v[104:105]
	v_pk_mul_f32 v[102:103], v[10:11], v[242:243] op_sel_hi:[1,0]
	v_pk_mul_f32 v[104:105], v[4:5], v[238:239] op_sel_hi:[1,0]
	v_pk_mul_f32 v[4:5], v[74:75], v[90:91]
	v_pk_fma_f32 v[10:11], v[84:85], v[88:89], v[2:3]
	v_pk_fma_f32 v[2:3], v[82:83], v[86:87], v[4:5]
	v_pk_fma_f32 v[4:5], v[104:105], v[80:81], v[10:11]
	v_pk_mul_f32 v[10:11], v[84:85], v[92:93]
	v_pk_mul_f32 v[50:51], v[106:107], v[50:51]
	v_pk_mul_f32 v[106:107], v[14:15], v[240:241] op_sel_hi:[1,0]
	v_pk_mul_f32 v[8:9], v[8:9], v[236:237] op_sel_hi:[1,0]
	v_pk_mul_f32 v[14:15], v[82:83], v[90:91]
	v_pk_fma_f32 v[74:75], v[104:105], v[88:89], v[10:11]
	v_pk_mul_f32 v[76:77], v[104:105], v[92:93]
	v_pk_mul_f32 v[12:13], v[12:13], v[242:243] op_sel_hi:[1,0]
	v_pk_fma_f32 v[10:11], v[108:109], v[86:87], v[14:15]
	v_pk_fma_f32 v[14:15], v[8:9], v[80:81], v[74:75]
	v_pk_fma_f32 v[76:77], v[8:9], v[88:89], v[76:77]
	v_pk_mul_f32 v[8:9], v[8:9], v[92:93]
	v_pk_mul_f32 v[6:7], v[6:7], v[236:237] op_sel_hi:[1,0]
	v_pk_fma_f32 v[8:9], v[12:13], v[88:89], v[8:9]
	v_pk_mul_f32 v[74:75], v[108:109], v[90:91]
	v_pk_fma_f32 v[84:85], v[16:17], v[80:81], v[8:9]
	v_pk_mul_f32 v[8:9], v[12:13], v[92:93]
	v_pk_fma_f32 v[10:11], v[6:7], v[78:79], v[10:11]
	v_pk_fma_f32 v[74:75], v[6:7], v[86:87], v[74:75]
	v_pk_mul_f32 v[6:7], v[6:7], v[90:91]
	v_pk_fma_f32 v[8:9], v[16:17], v[88:89], v[8:9]
	v_pk_fma_f32 v[6:7], v[102:103], v[86:87], v[6:7]
	v_pk_fma_f32 v[104:105], v[48:49], v[80:81], v[8:9]
	v_pk_mul_f32 v[8:9], v[16:17], v[92:93]
	v_pk_fma_f32 v[82:83], v[106:107], v[78:79], v[6:7]
	v_pk_mul_f32 v[6:7], v[102:103], v[90:91]
	v_pk_fma_f32 v[8:9], v[48:49], v[88:89], v[8:9]
	v_pk_fma_f32 v[2:3], v[108:109], v[78:79], v[2:3]
	v_pk_fma_f32 v[6:7], v[106:107], v[86:87], v[6:7]
	v_pk_fma_f32 v[108:109], v[44:45], v[80:81], v[8:9]
	v_pk_mul_f32 v[8:9], v[46:47], v[90:91]
	v_pk_fma_f32 v[74:75], v[102:103], v[78:79], v[74:75]
	v_pk_fma_f32 v[102:103], v[46:47], v[78:79], v[6:7]
	v_pk_mul_f32 v[6:7], v[106:107], v[90:91]
	v_pk_fma_f32 v[8:9], v[42:43], v[86:87], v[8:9]
	v_pk_fma_f32 v[6:7], v[46:47], v[86:87], v[6:7]
	v_pk_fma_f32 v[16:17], v[78:79], v[94:95], v[8:9]
	v_pk_mul_f32 v[8:9], v[86:87], v[94:95]
	v_pk_fma_f32 v[106:107], v[42:43], v[78:79], v[6:7]
	v_pk_fma_f32 v[8:9], v[42:43], v[90:91], v[8:9]
	v_pk_mul_f32 v[42:43], v[124:125], s[100:101] op_sel_hi:[1,0]
	v_exp_f32_e32 v42, v42
	v_exp_f32_e32 v43, v43
	v_pk_mul_f32 v[6:7], v[48:49], v[92:93]
	v_pk_fma_f32 v[76:77], v[12:13], v[80:81], v[76:77]
	v_pk_fma_f32 v[6:7], v[44:45], v[88:89], v[6:7]
	v_pk_add_f32 v[42:43], v[42:43], 1.0 op_sel_hi:[1,0]
	v_pk_fma_f32 v[12:13], v[80:81], v[96:97], v[6:7]
	v_pk_mul_f32 v[6:7], v[88:89], v[96:97]
	v_rcp_f32_e32 v42, v42
	v_rcp_f32_e32 v43, v43
	v_pk_fma_f32 v[6:7], v[44:45], v[92:93], v[6:7]
	v_pk_fma_f32 v[8:9], v[78:79], v[98:99], v[8:9]
	v_pk_fma_f32 v[6:7], v[80:81], v[100:101], v[6:7]
	v_pk_mul_f32 v[46:47], v[180:181], v[106:107]
	v_pk_mul_f32 v[44:45], v[122:123], v[6:7]
	v_pk_mul_f32 v[6:7], v[124:125], v[8:9]
	v_pk_mul_f32 v[8:9], v[122:123], s[100:101] op_sel_hi:[1,0]
	v_pk_mul_f32 v[6:7], v[42:43], v[6:7]
	v_exp_f32_e32 v8, v8
	v_exp_f32_e32 v9, v9
	v_pk_mul_f32 v[42:43], v[128:129], s[100:101] op_sel_hi:[1,0]
	v_exp_f32_e32 v42, v42
	v_exp_f32_e32 v43, v43
	v_pk_add_f32 v[8:9], v[8:9], 1.0 op_sel_hi:[1,0]
	v_rcp_f32_e32 v8, v8
	v_rcp_f32_e32 v9, v9
	v_pk_add_f32 v[42:43], v[42:43], 1.0 op_sel_hi:[1,0]
	v_rcp_f32_e32 v42, v42
	v_rcp_f32_e32 v43, v43
	v_pk_mul_f32 v[8:9], v[8:9], v[44:45]
	v_pk_mul_f32 v[44:45], v[126:127], v[12:13]
	v_pk_mul_f32 v[12:13], v[128:129], v[16:17]
	v_mul_f32_e32 v16, 0xbfb8aa3b, v126
	v_pk_mul_f32 v[12:13], v[42:43], v[12:13]
	v_pk_mul_f32 v[42:43], v[180:181], s[100:101] op_sel_hi:[1,0]
	v_exp_f32_e32 v42, v42
	v_exp_f32_e32 v43, v43
	v_mul_f32_e32 v17, 0xbfb8aa3b, v127
	v_exp_f32_e32 v16, v16
	v_pk_add_f32 v[42:43], v[42:43], 1.0 op_sel_hi:[1,0]
	v_rcp_f32_e32 v42, v42
	v_rcp_f32_e32 v43, v43
	v_exp_f32_e32 v17, v17
	v_add_f32_e32 v16, 1.0, v16
	v_pk_mul_f32 v[14:15], v[62:63], v[14:15]
	v_pk_mul_f32 v[42:43], v[42:43], v[46:47]
	v_pk_mul_f32 v[46:47], v[178:179], s[100:101] op_sel_hi:[1,0]
	v_exp_f32_e32 v46, v46
	v_exp_f32_e32 v47, v47
	v_add_f32_e32 v17, 1.0, v17
	v_pk_mul_f32 v[62:63], v[62:63], s[100:101] op_sel_hi:[1,0]
	v_rcp_f32_e32 v16, v16
	v_rcp_f32_e32 v17, v17
	v_pk_add_f32 v[46:47], v[46:47], 1.0 op_sel_hi:[1,0]
	v_exp_f32_e32 v62, v62
	v_exp_f32_e32 v63, v63
	v_rcp_f32_e32 v46, v46
	v_rcp_f32_e32 v47, v47
	v_pk_mul_f32 v[16:17], v[16:17], v[44:45]
	v_pk_mul_f32 v[44:45], v[178:179], v[108:109]
	v_pk_add_f32 v[62:63], v[62:63], 1.0 op_sel_hi:[1,0]
	v_pk_mul_f32 v[44:45], v[46:47], v[44:45]
	v_pk_mul_f32 v[46:47], v[156:157], s[100:101] op_sel_hi:[1,0]
	v_rcp_f32_e32 v62, v62
	v_rcp_f32_e32 v63, v63
	v_exp_f32_e32 v46, v46
	v_exp_f32_e32 v47, v47
	v_pk_mul_f32 v[78:79], v[156:157], v[102:103]
	v_pk_mul_f32 v[14:15], v[62:63], v[14:15]
	v_pk_mul_f32 v[62:63], v[60:61], s[100:101] op_sel_hi:[1,0]
	v_pk_add_f32 v[46:47], v[46:47], 1.0 op_sel_hi:[1,0]
	v_exp_f32_e32 v62, v62
	v_exp_f32_e32 v63, v63
	v_rcp_f32_e32 v46, v46
	v_rcp_f32_e32 v47, v47
	v_pk_add_f32 v[62:63], v[62:63], 1.0 op_sel_hi:[1,0]
	v_rcp_f32_e32 v62, v62
	v_pk_mul_f32 v[46:47], v[46:47], v[78:79]
	v_pk_mul_f32 v[78:79], v[154:155], s[100:101] op_sel_hi:[1,0]
	v_rcp_f32_e32 v63, v63
	v_exp_f32_e32 v78, v78
	v_exp_f32_e32 v79, v79
	v_pk_mul_f32 v[2:3], v[60:61], v[2:3]
	v_pk_mul_f32 v[48:49], v[154:155], v[104:105]
	v_pk_mul_f32 v[60:61], v[62:63], v[2:3]
	v_pk_mul_f32 v[2:3], v[58:59], s[100:101] op_sel_hi:[1,0]
	v_pk_add_f32 v[78:79], v[78:79], 1.0 op_sel_hi:[1,0]
	v_exp_f32_e32 v2, v2
	v_exp_f32_e32 v3, v3
	v_rcp_f32_e32 v78, v78
	v_rcp_f32_e32 v79, v79
	v_pk_add_f32 v[2:3], v[2:3], 1.0 op_sel_hi:[1,0]
	v_rcp_f32_e32 v2, v2
	v_pk_mul_f32 v[48:49], v[78:79], v[48:49]
	v_pk_mul_f32 v[78:79], v[72:73], s[100:101] op_sel_hi:[1,0]
	v_rcp_f32_e32 v3, v3
	v_exp_f32_e32 v78, v78
	v_exp_f32_e32 v79, v79
	v_pk_mul_f32 v[4:5], v[58:59], v[4:5]
	v_pk_mul_f32 v[80:81], v[70:71], v[84:85]
	v_pk_mul_f32 v[58:59], v[2:3], v[4:5]
	v_cvt_pk_bf16_f32 v4, v6, v7
	v_lshrrev_b32_e32 v130, 2, v213
	v_and_b32_e32 v131, 3, v213
	v_lshlrev_b32_e32 v134, 6, v131
	v_lshl_add_u32 v134, v130, 2, v134
	v_sub_u32_e32 v135, v130, v249
	v_lshl_add_u32 v135, v135, 3, v232
	v_sub_u32_e32 v136, v131, v250
	v_lshl_add_u32 v132, v136, 3, v234
	v_mov_b32_e32 v133, v235
	v_lshlrev_b64 v[132:133], 1, v[132:133]
	v_mov_b64_e32 v[6:7], s[46:47]
	v_add_f32_e32 v78, 1.0, v78
	v_add_f32_e32 v79, 1.0, v79
	v_cvt_pk_bf16_f32 v2, v18, v19
	v_cvt_pk_bf16_f32 v5, v8, v9
	v_mad_i64_i32 v[8:9], s[4:5], v135, s92, v[6:7]
	v_lshlrev_b64 v[18:19], 1, v[234:235]
	v_rcp_f32_e32 v78, v78
	v_rcp_f32_e32 v79, v79
	v_cvt_pk_bf16_f32 v3, v20, v21
	v_lshl_add_u64 v[8:9], v[8:9], 0, v[132:133]
	v_mul_f32_e32 v70, 0xbfb8aa3b, v70
	v_mul_f32_e32 v71, 0xbfb8aa3b, v71
	ds_bpermute_b32 v138, v134, v2
	ds_bpermute_b32 v139, v134, v3
	ds_bpermute_b32 v140, v134, v4
	ds_bpermute_b32 v141, v134, v5
	v_mov_b64_e32 v[146:147], v[8:9]
	v_or_b32_e32 v8, 1, v135
	v_exp_f32_e32 v70, v70
	v_exp_f32_e32 v71, v71
	v_mad_i64_i32 v[8:9], s[4:5], v8, s92, v[6:7]
	v_pk_mul_f32 v[72:73], v[72:73], v[82:83]
	v_cvt_pk_bf16_f32 v2, v22, v23
	v_cvt_pk_bf16_f32 v3, v24, v25
	v_cvt_pk_bf16_f32 v4, v12, v13
	v_cvt_pk_bf16_f32 v5, v16, v17
	v_lshl_add_u64 v[8:9], v[8:9], 0, v[132:133]
	v_pk_mul_f32 v[72:73], v[78:79], v[72:73]
	v_mul_f32_e32 v78, 0xbfb8aa3b, v68
	v_mul_f32_e32 v79, 0xbfb8aa3b, v69
	v_pk_mul_f32 v[76:77], v[66:67], v[76:77]
	v_mul_f32_e32 v66, 0xbfb8aa3b, v66
	v_mul_f32_e32 v67, 0xbfb8aa3b, v67
	ds_bpermute_b32 v142, v134, v2
	ds_bpermute_b32 v143, v134, v3
	ds_bpermute_b32 v144, v134, v4
	ds_bpermute_b32 v145, v134, v5
	v_mov_b64_e32 v[148:149], v[8:9]
	s_waitcnt lgkmcnt(4)
	global_store_dwordx4 v[146:147], v[138:141], off
	v_or_b32_e32 v8, 2, v135
	v_exp_f32_e32 v78, v78
	v_exp_f32_e32 v79, v79
	v_exp_f32_e32 v66, v66
	v_exp_f32_e32 v67, v67
	v_mad_i64_i32 v[8:9], s[4:5], v8, s92, v[6:7]
	v_add_f32_e32 v70, 1.0, v70
	v_add_f32_e32 v71, 1.0, v71
	v_cvt_pk_bf16_f32 v2, v26, v27
	v_cvt_pk_bf16_f32 v3, v28, v29
	v_cvt_pk_bf16_f32 v4, v42, v43
	v_cvt_pk_bf16_f32 v5, v44, v45
	v_lshl_add_u64 v[8:9], v[8:9], 0, v[132:133]
	v_rcp_f32_e32 v70, v70
	v_rcp_f32_e32 v71, v71
	v_pk_mul_f32 v[68:69], v[68:69], v[74:75]
	v_mul_f32_e32 v74, 0xbfb8aa3b, v64
	v_mul_f32_e32 v75, 0xbfb8aa3b, v65
	ds_bpermute_b32 v138, v134, v2
	ds_bpermute_b32 v139, v134, v3
	ds_bpermute_b32 v140, v134, v4
	ds_bpermute_b32 v141, v134, v5
	v_mov_b64_e32 v[146:147], v[8:9]
	s_waitcnt lgkmcnt(4)
	global_store_dwordx4 v[148:149], v[142:145], off
	v_or_b32_e32 v8, 3, v135
	v_exp_f32_e32 v74, v74
	v_exp_f32_e32 v75, v75
	v_mad_i64_i32 v[8:9], s[4:5], v8, s92, v[6:7]
	v_add_f32_e32 v78, 1.0, v78
	v_add_f32_e32 v79, 1.0, v79
	v_add_f32_e32 v66, 1.0, v66
	v_add_f32_e32 v67, 1.0, v67
	v_cvt_pk_bf16_f32 v2, v30, v31
	v_cvt_pk_bf16_f32 v3, v32, v33
	v_cvt_pk_bf16_f32 v4, v46, v47
	v_cvt_pk_bf16_f32 v5, v48, v49
	v_lshl_add_u64 v[8:9], v[8:9], 0, v[132:133]
	v_rcp_f32_e32 v78, v78
	v_rcp_f32_e32 v79, v79
	v_rcp_f32_e32 v66, v66
	v_rcp_f32_e32 v67, v67
	ds_bpermute_b32 v142, v134, v2
	ds_bpermute_b32 v143, v134, v3
	ds_bpermute_b32 v144, v134, v4
	ds_bpermute_b32 v145, v134, v5
	v_mov_b64_e32 v[148:149], v[8:9]
	s_waitcnt lgkmcnt(4)
	global_store_dwordx4 v[146:147], v[138:141], off
	v_or_b32_e32 v8, 4, v135
	v_pk_mul_f32 v[70:71], v[70:71], v[80:81]
	v_mad_i64_i32 v[8:9], s[4:5], v8, s92, v[6:7]
	v_add_f32_e32 v74, 1.0, v74
	v_add_f32_e32 v75, 1.0, v75
	v_cvt_pk_bf16_f32 v2, v34, v35
	v_cvt_pk_bf16_f32 v3, v36, v37
	v_cvt_pk_bf16_f32 v4, v72, v73
	v_cvt_pk_bf16_f32 v5, v70, v71
	v_lshl_add_u64 v[8:9], v[8:9], 0, v[132:133]
	v_rcp_f32_e32 v74, v74
	v_rcp_f32_e32 v75, v75
	ds_bpermute_b32 v138, v134, v2
	ds_bpermute_b32 v139, v134, v3
	ds_bpermute_b32 v140, v134, v4
	ds_bpermute_b32 v141, v134, v5
	v_mov_b64_e32 v[146:147], v[8:9]
	s_waitcnt lgkmcnt(4)
	global_store_dwordx4 v[148:149], v[142:145], off
	v_or_b32_e32 v8, 5, v135
	v_pk_mul_f32 v[68:69], v[78:79], v[68:69]
	v_pk_mul_f32 v[66:67], v[66:67], v[76:77]
	v_mad_i64_i32 v[8:9], s[4:5], v8, s92, v[6:7]
	v_cvt_pk_bf16_f32 v2, v38, v39
	v_cvt_pk_bf16_f32 v3, v40, v41
	v_cvt_pk_bf16_f32 v4, v68, v69
	v_cvt_pk_bf16_f32 v5, v66, v67
	v_lshl_add_u64 v[8:9], v[8:9], 0, v[132:133]
	v_pk_mul_f32 v[10:11], v[64:65], v[10:11]
	ds_bpermute_b32 v142, v134, v2
	ds_bpermute_b32 v143, v134, v3
	ds_bpermute_b32 v144, v134, v4
	ds_bpermute_b32 v145, v134, v5
	v_mov_b64_e32 v[148:149], v[8:9]
	s_waitcnt lgkmcnt(4)
	global_store_dwordx4 v[146:147], v[138:141], off
	v_or_b32_e32 v8, 6, v135
	v_pk_mul_f32 v[10:11], v[74:75], v[10:11]
	v_mad_i64_i32 v[8:9], s[4:5], v8, s92, v[6:7]
	v_cvt_pk_bf16_f32 v2, v50, v51
	v_cvt_pk_bf16_f32 v3, v52, v53
	v_cvt_pk_bf16_f32 v4, v10, v11
	v_cvt_pk_bf16_f32 v5, v14, v15
	v_lshl_add_u64 v[8:9], v[8:9], 0, v[132:133]
	ds_bpermute_b32 v138, v134, v2
	ds_bpermute_b32 v139, v134, v3
	ds_bpermute_b32 v140, v134, v4
	ds_bpermute_b32 v141, v134, v5
	v_mov_b64_e32 v[146:147], v[8:9]
	s_waitcnt lgkmcnt(4)
	global_store_dwordx4 v[148:149], v[142:145], off
	v_or_b32_e32 v8, 7, v135
	v_mad_i64_i32 v[6:7], s[4:5], v8, s92, v[6:7]
	v_cvt_pk_bf16_f32 v2, v54, v55
	v_cvt_pk_bf16_f32 v3, v56, v57
	v_cvt_pk_bf16_f32 v4, v60, v61
	v_cvt_pk_bf16_f32 v5, v58, v59
	v_lshl_add_u64 v[6:7], v[6:7], 0, v[132:133]
	ds_bpermute_b32 v142, v134, v2
	ds_bpermute_b32 v143, v134, v3
	ds_bpermute_b32 v144, v134, v4
	ds_bpermute_b32 v145, v134, v5
	v_mov_b64_e32 v[148:149], v[6:7]
	s_waitcnt lgkmcnt(4)
	global_store_dwordx4 v[146:147], v[138:141], off
	s_andn2_b64 vcc, exec, s[40:41]
	s_waitcnt lgkmcnt(0)
	global_store_dwordx4 v[148:149], v[142:145], off
	s_cbranch_vccnz .LBB0_386
	s_andn2_b64 vcc, exec, s[24:25]
	s_cbranch_vccnz .LBB0_385
	s_barrier
	s_branch .LBB0_385
